# y_b GEMM epilogue: streaming (nt) hint on the once-read gate_b tile loads (written three phases earlier)
# baseline (speedup 1.0000x reference)
.LBB0_885:
	s_lshl_b32 s2, s54, 8
	v_mbcnt_lo_u32_b32 v3, -1, 0
	v_mbcnt_hi_u32_b32 v3, -1, v3
	s_add_i32 s2, s2, s39
	v_and_or_b32 v2, v3, 15, s2
	s_lshl_b32 s2, s64, 8
	v_ashrrev_i32_e32 v3, 1, v3
	s_or_b32 s2, s2, s40
	v_and_b32_e32 v3, -8, v3
	v_add_u32_e32 v4, s2, v3
	v_ashrrev_i32_e32 v5, 31, v4
	v_lshlrev_b64 v[10:11], 1, v[4:5]
	v_ashrrev_i32_e32 v3, 31, v2
	v_lshl_add_u64 v[6:7], s[12:13], 0, v[10:11]
	v_lshlrev_b64 v[8:9], 12, v[2:3]
	v_lshl_add_u64 v[4:5], v[6:7], 0, v[8:9]
	global_load_dwordx4 v[14:17], v[4:5], off nt
	global_load_dwordx4 v[18:21], v[4:5], off offset:256 nt
	v_or_b32_e32 v4, 16, v2
	v_ashrrev_i32_e32 v5, 31, v4
	v_lshlrev_b64 v[178:179], 12, v[4:5]
	v_lshl_add_u64 v[4:5], v[6:7], 0, v[178:179]
	global_load_dwordx4 v[22:25], v[4:5], off nt
	global_load_dwordx4 v[26:29], v[4:5], off offset:256 nt
	v_or_b32_e32 v4, 32, v2
	v_ashrrev_i32_e32 v5, 31, v4
	v_lshlrev_b64 v[194:195], 12, v[4:5]
	v_lshl_add_u64 v[4:5], v[6:7], 0, v[194:195]
	global_load_dwordx4 v[30:33], v[4:5], off nt
	v_or_b32_e32 v2, 48, v2
	v_ashrrev_i32_e32 v3, 31, v2
	v_lshlrev_b64 v[12:13], 12, v[2:3]
	v_lshl_add_u64 v[2:3], s[16:17], 0, v[8:9]
	v_lshl_add_u64 v[196:197], v[2:3], 0, v[10:11]
	v_lshl_add_u64 v[2:3], v[6:7], 0, v[12:13]
	v_pk_mul_f32 v[180:181], v[144:145], s[22:23] op_sel_hi:[1,0]
	v_pk_mul_f32 v[182:183], v[142:143], s[22:23] op_sel_hi:[1,0]
	v_pk_mul_f32 v[184:185], v[140:141], s[22:23] op_sel_hi:[1,0]
	v_pk_mul_f32 v[192:193], v[138:139], s[22:23] op_sel_hi:[1,0]
	global_load_dwordx4 v[138:141], v[4:5], off offset:256 nt
	global_load_dwordx4 v[142:145], v[2:3], off nt
	s_nop 0
	global_load_dwordx4 v[2:5], v[2:3], off offset:256 nt
	v_pk_mul_f32 v[160:161], v[160:161], s[22:23] op_sel_hi:[1,0]
	v_pk_mul_f32 v[158:159], v[158:159], s[22:23] op_sel_hi:[1,0]
	v_pk_mul_f32 v[156:157], v[156:157], s[22:23] op_sel_hi:[1,0]
	v_pk_mul_f32 v[154:155], v[154:155], s[22:23] op_sel_hi:[1,0]
	v_pk_mul_f32 v[152:153], v[152:153], s[22:23] op_sel_hi:[1,0]
	v_pk_mul_f32 v[150:151], v[150:151], s[22:23] op_sel_hi:[1,0]
	v_pk_mul_f32 v[148:149], v[148:149], s[22:23] op_sel_hi:[1,0]
	v_pk_mul_f32 v[146:147], v[146:147], s[22:23] op_sel_hi:[1,0]
	v_lshl_add_u64 v[12:13], s[16:17], 0, v[12:13]
	v_lshl_add_u64 v[12:13], v[12:13], 0, v[10:11]
	v_pk_mul_f32 v[96:97], v[96:97], s[22:23] op_sel_hi:[1,0]
	v_pk_mul_f32 v[94:95], v[94:95], s[22:23] op_sel_hi:[1,0]
	v_pk_mul_f32 v[92:93], v[92:93], s[22:23] op_sel_hi:[1,0]
	v_pk_mul_f32 v[90:91], v[90:91], s[22:23] op_sel_hi:[1,0]
	v_pk_mul_f32 v[86:87], v[86:87], s[22:23] op_sel_hi:[1,0]
	v_pk_mul_f32 v[88:89], v[88:89], s[22:23] op_sel_hi:[1,0]
	v_pk_mul_f32 v[84:85], v[84:85], s[22:23] op_sel_hi:[1,0]
	v_pk_mul_f32 v[82:83], v[82:83], s[22:23] op_sel_hi:[1,0]
	s_andn2_b64 vcc, exec, s[4:5]
	s_mov_b64 s[4:5], -1
	s_waitcnt vmcnt(0)
	v_lshlrev_b32_e32 v198, 16, v14
	v_and_b32_e32 v199, 0xffff0000, v14
	v_lshlrev_b32_e32 v14, 16, v15
	v_and_b32_e32 v15, 0xffff0000, v15
	v_lshlrev_b32_e32 v200, 16, v16
	v_and_b32_e32 v201, 0xffff0000, v16
	v_lshlrev_b32_e32 v16, 16, v17
	v_and_b32_e32 v17, 0xffff0000, v17
	v_pk_mul_f32 v[160:161], v[160:161], v[14:15]
	v_pk_mul_f32 v[14:15], v[158:159], v[198:199]
	v_pk_mul_f32 v[156:157], v[156:157], v[16:17]
	v_pk_mul_f32 v[16:17], v[154:155], v[200:201]
	v_lshlrev_b32_e32 v202, 16, v18
	v_and_b32_e32 v203, 0xffff0000, v18
	v_lshlrev_b32_e32 v18, 16, v19
	v_and_b32_e32 v19, 0xffff0000, v19
	v_lshlrev_b32_e32 v204, 16, v20
	v_and_b32_e32 v205, 0xffff0000, v20
	v_lshlrev_b32_e32 v20, 16, v21
	v_and_b32_e32 v21, 0xffff0000, v21
	v_cvt_pk_bf16_f32 v14, v14, v15
	v_cvt_pk_bf16_f32 v15, v160, v161
	v_cvt_pk_bf16_f32 v16, v16, v17
	v_cvt_pk_bf16_f32 v17, v156, v157
	v_lshlrev_b32_e32 v208, 16, v24
	v_and_b32_e32 v209, 0xffff0000, v24
	v_lshlrev_b32_e32 v24, 16, v25
	v_and_b32_e32 v25, 0xffff0000, v25
	v_pk_mul_f32 v[18:19], v[152:153], v[18:19]
	v_pk_mul_f32 v[150:151], v[150:151], v[202:203]
	v_pk_mul_f32 v[20:21], v[148:149], v[20:21]
	v_pk_mul_f32 v[146:147], v[146:147], v[204:205]
	global_store_dwordx4 v[196:197], v[14:17], off
	v_lshlrev_b32_e32 v206, 16, v22
	v_and_b32_e32 v207, 0xffff0000, v22
	v_cvt_pk_bf16_f32 v14, v150, v151
	v_cvt_pk_bf16_f32 v15, v18, v19
	v_cvt_pk_bf16_f32 v16, v146, v147
	v_cvt_pk_bf16_f32 v17, v20, v21
	v_lshlrev_b32_e32 v22, 16, v23
	v_and_b32_e32 v23, 0xffff0000, v23
	global_store_dwordx4 v[196:197], v[14:17], off offset:256
	v_pk_mul_f32 v[18:19], v[184:185], v[24:25]
	v_pk_mul_f32 v[22:23], v[180:181], v[22:23]
	v_pk_mul_f32 v[16:17], v[192:193], v[208:209]
	v_pk_mul_f32 v[148:149], v[182:183], v[206:207]
	v_pk_mul_f32 v[24:25], v[136:137], s[22:23] op_sel_hi:[1,0]
	v_cvt_pk_bf16_f32 v14, v148, v149
	v_cvt_pk_bf16_f32 v15, v22, v23
	v_cvt_pk_bf16_f32 v16, v16, v17
	v_cvt_pk_bf16_f32 v17, v18, v19
	v_lshl_add_u64 v[18:19], s[16:17], 0, v[178:179]
	v_lshl_add_u64 v[18:19], v[18:19], 0, v[10:11]
	global_store_dwordx4 v[18:19], v[14:17], off
	v_lshlrev_b32_e32 v20, 16, v28
	v_and_b32_e32 v21, 0xffff0000, v28
	v_lshlrev_b32_e32 v14, 16, v26
	v_and_b32_e32 v15, 0xffff0000, v26
	v_lshlrev_b32_e32 v16, 16, v27
	v_and_b32_e32 v17, 0xffff0000, v27
	v_pk_mul_f32 v[26:27], v[134:135], s[22:23] op_sel_hi:[1,0]
	v_lshlrev_b32_e32 v22, 16, v29
	v_pk_mul_f32 v[14:15], v[26:27], v[14:15]
	v_and_b32_e32 v23, 0xffff0000, v29
	v_pk_mul_f32 v[16:17], v[24:25], v[16:17]
	v_pk_mul_f32 v[24:25], v[132:133], s[22:23] op_sel_hi:[1,0]
	v_pk_mul_f32 v[26:27], v[130:131], s[22:23] op_sel_hi:[1,0]
	v_cvt_pk_bf16_f32 v14, v14, v15
	v_cvt_pk_bf16_f32 v15, v16, v17
	v_pk_mul_f32 v[22:23], v[24:25], v[22:23]
	v_pk_mul_f32 v[20:21], v[26:27], v[20:21]
	v_pk_mul_f32 v[24:25], v[126:127], s[22:23] op_sel_hi:[1,0]
	v_cvt_pk_bf16_f32 v16, v20, v21
	v_cvt_pk_bf16_f32 v17, v22, v23
	global_store_dwordx4 v[18:19], v[14:17], off offset:256
	v_lshlrev_b32_e32 v18, 16, v32
	v_and_b32_e32 v19, 0xffff0000, v32
	v_lshlrev_b32_e32 v14, 16, v30
	v_and_b32_e32 v15, 0xffff0000, v30
	v_lshlrev_b32_e32 v16, 16, v31
	v_and_b32_e32 v17, 0xffff0000, v31
	v_pk_mul_f32 v[22:23], v[128:129], s[22:23] op_sel_hi:[1,0]
	v_pk_mul_f32 v[14:15], v[24:25], v[14:15]
	v_pk_mul_f32 v[24:25], v[122:123], s[22:23] op_sel_hi:[1,0]
	v_pk_mul_f32 v[16:17], v[22:23], v[16:17]
	v_pk_mul_f32 v[18:19], v[24:25], v[18:19]
	v_lshlrev_b32_e32 v20, 16, v33
	v_and_b32_e32 v21, 0xffff0000, v33
	v_pk_mul_f32 v[22:23], v[124:125], s[22:23] op_sel_hi:[1,0]
	v_cvt_pk_bf16_f32 v14, v14, v15
	v_cvt_pk_bf16_f32 v15, v16, v17
	v_cvt_pk_bf16_f32 v16, v18, v19
	v_lshl_add_u64 v[18:19], s[16:17], 0, v[194:195]
	v_pk_mul_f32 v[20:21], v[22:23], v[20:21]
	v_lshl_add_u64 v[18:19], v[18:19], 0, v[10:11]
	v_cvt_pk_bf16_f32 v17, v20, v21
	global_store_dwordx4 v[18:19], v[14:17], off
	v_pk_mul_f32 v[24:25], v[120:121], s[22:23] op_sel_hi:[1,0]
	v_pk_mul_f32 v[26:27], v[118:119], s[22:23] op_sel_hi:[1,0]
	v_lshlrev_b32_e32 v14, 16, v138
	v_and_b32_e32 v15, 0xffff0000, v138
	v_lshlrev_b32_e32 v16, 16, v139
	v_and_b32_e32 v17, 0xffff0000, v139
	v_lshlrev_b32_e32 v20, 16, v140
	v_and_b32_e32 v21, 0xffff0000, v140
	v_lshlrev_b32_e32 v22, 16, v141
	v_and_b32_e32 v23, 0xffff0000, v141
	v_pk_mul_f32 v[16:17], v[24:25], v[16:17]
	v_pk_mul_f32 v[14:15], v[26:27], v[14:15]
	v_pk_mul_f32 v[24:25], v[116:117], s[22:23] op_sel_hi:[1,0]
	v_pk_mul_f32 v[26:27], v[114:115], s[22:23] op_sel_hi:[1,0]
	v_pk_mul_f32 v[22:23], v[24:25], v[22:23]
	v_pk_mul_f32 v[20:21], v[26:27], v[20:21]
	v_cvt_pk_bf16_f32 v14, v14, v15
	v_cvt_pk_bf16_f32 v15, v16, v17
	v_pk_mul_f32 v[24:25], v[110:111], s[22:23] op_sel_hi:[1,0]
	v_cvt_pk_bf16_f32 v16, v20, v21
	v_cvt_pk_bf16_f32 v17, v22, v23
	global_store_dwordx4 v[18:19], v[14:17], off offset:256
	v_pk_mul_f32 v[22:23], v[112:113], s[22:23] op_sel_hi:[1,0]
	v_lshlrev_b32_e32 v18, 16, v144
	v_lshlrev_b32_e32 v14, 16, v142
	v_and_b32_e32 v15, 0xffff0000, v142
	v_lshlrev_b32_e32 v16, 16, v143
	v_and_b32_e32 v17, 0xffff0000, v143
	v_and_b32_e32 v19, 0xffff0000, v144
	v_lshlrev_b32_e32 v20, 16, v145
	v_and_b32_e32 v21, 0xffff0000, v145
	v_pk_mul_f32 v[16:17], v[22:23], v[16:17]
	v_pk_mul_f32 v[14:15], v[24:25], v[14:15]
	v_pk_mul_f32 v[22:23], v[108:109], s[22:23] op_sel_hi:[1,0]
	v_pk_mul_f32 v[24:25], v[106:107], s[22:23] op_sel_hi:[1,0]
	v_pk_mul_f32 v[20:21], v[22:23], v[20:21]
	v_pk_mul_f32 v[18:19], v[24:25], v[18:19]
	v_cvt_pk_bf16_f32 v14, v14, v15
	v_cvt_pk_bf16_f32 v15, v16, v17
	v_lshl_add_u64 v[106:107], v[8:9], 0, s[28:29]
	v_cvt_pk_bf16_f32 v16, v18, v19
	v_cvt_pk_bf16_f32 v17, v20, v21
	global_store_dwordx4 v[12:13], v[14:17], off
	v_pk_mul_f32 v[18:19], v[104:105], s[22:23] op_sel_hi:[1,0]
	v_pk_mul_f32 v[20:21], v[102:103], s[22:23] op_sel_hi:[1,0]
	v_lshlrev_b32_e32 v14, 16, v2
	v_and_b32_e32 v15, 0xffff0000, v2
	v_lshlrev_b32_e32 v2, 16, v3
	v_and_b32_e32 v3, 0xffff0000, v3
	v_lshlrev_b32_e32 v16, 16, v4
	v_and_b32_e32 v17, 0xffff0000, v4
	v_lshlrev_b32_e32 v4, 16, v5
	v_and_b32_e32 v5, 0xffff0000, v5
	v_pk_mul_f32 v[18:19], v[18:19], v[2:3]
	v_pk_mul_f32 v[2:3], v[20:21], v[14:15]
	v_pk_mul_f32 v[14:15], v[100:101], s[22:23] op_sel_hi:[1,0]
	v_pk_mul_f32 v[20:21], v[98:99], s[22:23] op_sel_hi:[1,0]
	v_lshl_add_u64 v[102:103], v[8:9], 0, s[24:25]
	v_pk_mul_f32 v[14:15], v[14:15], v[4:5]
	v_pk_mul_f32 v[4:5], v[20:21], v[16:17]
	v_cvt_pk_bf16_f32 v2, v2, v3
	v_cvt_pk_bf16_f32 v3, v18, v19
	v_lshl_add_u64 v[18:19], v[6:7], 0, v[102:103]
	v_cvt_pk_bf16_f32 v4, v4, v5
	v_cvt_pk_bf16_f32 v5, v14, v15
	global_load_dwordx4 v[14:17], v[18:19], off nt
	s_nop 0
	global_load_dwordx4 v[18:21], v[18:19], off offset:256 nt
	v_lshl_add_u64 v[104:105], v[8:9], 0, s[26:27]
	v_lshl_add_u64 v[26:27], v[6:7], 0, v[104:105]
	global_load_dwordx4 v[22:25], v[26:27], off nt
	s_nop 0
	global_load_dwordx4 v[26:29], v[26:27], off offset:256 nt
	s_waitcnt vmcnt(3)
	v_lshlrev_b32_e32 v108, 16, v14
	global_store_dwordx4 v[12:13], v[2:5], off offset:256
	v_lshl_add_u64 v[12:13], v[8:9], 0, s[30:31]
	v_and_b32_e32 v109, 0xffff0000, v14
	v_lshl_add_u64 v[2:3], v[6:7], 0, v[106:107]
	global_load_dwordx4 v[30:33], v[2:3], off nt
	global_load_dwordx4 v[98:101], v[2:3], off offset:256 nt
	v_lshl_add_u64 v[2:3], v[6:7], 0, v[12:13]
	global_load_dwordx4 v[6:9], v[2:3], off nt
	s_nop 0
	global_load_dwordx4 v[2:5], v[2:3], off offset:256 nt
	v_lshlrev_b32_e32 v14, 16, v15
	v_and_b32_e32 v15, 0xffff0000, v15
	v_lshlrev_b32_e32 v110, 16, v16
	v_and_b32_e32 v111, 0xffff0000, v16
	v_lshlrev_b32_e32 v16, 16, v17
	v_and_b32_e32 v17, 0xffff0000, v17
	v_pk_mul_f32 v[96:97], v[96:97], v[14:15]
	v_pk_mul_f32 v[14:15], v[94:95], v[108:109]
	v_pk_mul_f32 v[92:93], v[92:93], v[16:17]
	v_pk_mul_f32 v[16:17], v[90:91], v[110:111]
	v_lshl_add_u64 v[90:91], s[16:17], 0, v[102:103]
	v_cvt_pk_bf16_f32 v14, v14, v15
	v_cvt_pk_bf16_f32 v15, v96, v97
	v_lshl_add_u64 v[90:91], v[90:91], 0, v[10:11]
	v_cvt_pk_bf16_f32 v16, v16, v17
	v_cvt_pk_bf16_f32 v17, v92, v93
	global_store_dwordx4 v[90:91], v[14:17], off
	v_lshl_add_u64 v[12:13], s[16:17], 0, v[12:13]
	s_waitcnt vmcnt(8)
	v_lshlrev_b32_e32 v14, 16, v18
	v_and_b32_e32 v15, 0xffff0000, v18
	v_lshlrev_b32_e32 v16, 16, v19
	v_and_b32_e32 v17, 0xffff0000, v19
	v_lshlrev_b32_e32 v18, 16, v20
	v_and_b32_e32 v19, 0xffff0000, v20
	v_lshlrev_b32_e32 v20, 16, v21
	v_and_b32_e32 v21, 0xffff0000, v21
	v_pk_mul_f32 v[14:15], v[86:87], v[14:15]
	v_pk_mul_f32 v[16:17], v[88:89], v[16:17]
	v_pk_mul_f32 v[20:21], v[84:85], v[20:21]
	v_pk_mul_f32 v[18:19], v[82:83], v[18:19]
	v_cvt_pk_bf16_f32 v14, v14, v15
	v_cvt_pk_bf16_f32 v15, v16, v17
	s_nop 0
	v_cvt_pk_bf16_f32 v16, v18, v19
	v_cvt_pk_bf16_f32 v17, v20, v21
	global_store_dwordx4 v[90:91], v[14:17], off offset:256
	s_waitcnt vmcnt(8)
	v_lshlrev_b32_e32 v18, 16, v24
	v_and_b32_e32 v19, 0xffff0000, v24
	v_lshlrev_b32_e32 v14, 16, v22
	v_and_b32_e32 v15, 0xffff0000, v22
	v_lshlrev_b32_e32 v20, 16, v25
	v_and_b32_e32 v21, 0xffff0000, v25
	v_pk_mul_f32 v[24:25], v[78:79], s[22:23] op_sel_hi:[1,0]
	v_lshlrev_b32_e32 v16, 16, v23
	v_and_b32_e32 v17, 0xffff0000, v23
	v_pk_mul_f32 v[22:23], v[80:81], s[22:23] op_sel_hi:[1,0]
	v_pk_mul_f32 v[14:15], v[24:25], v[14:15]
	v_pk_mul_f32 v[24:25], v[74:75], s[22:23] op_sel_hi:[1,0]
	v_pk_mul_f32 v[16:17], v[22:23], v[16:17]
	v_pk_mul_f32 v[18:19], v[24:25], v[18:19]
	v_pk_mul_f32 v[22:23], v[76:77], s[22:23] op_sel_hi:[1,0]
	v_cvt_pk_bf16_f32 v14, v14, v15
	v_cvt_pk_bf16_f32 v15, v16, v17
	v_cvt_pk_bf16_f32 v16, v18, v19
	v_lshl_add_u64 v[18:19], s[16:17], 0, v[104:105]
	v_pk_mul_f32 v[20:21], v[22:23], v[20:21]
	v_lshl_add_u64 v[18:19], v[18:19], 0, v[10:11]
	v_cvt_pk_bf16_f32 v17, v20, v21
	global_store_dwordx4 v[18:19], v[14:17], off
	v_pk_mul_f32 v[24:25], v[72:73], s[22:23] op_sel_hi:[1,0]
	s_waitcnt vmcnt(8)
	v_lshlrev_b32_e32 v20, 16, v28
	v_lshlrev_b32_e32 v14, 16, v26
	v_and_b32_e32 v15, 0xffff0000, v26
	v_lshlrev_b32_e32 v16, 16, v27
	v_and_b32_e32 v17, 0xffff0000, v27
	v_pk_mul_f32 v[26:27], v[70:71], s[22:23] op_sel_hi:[1,0]
	v_and_b32_e32 v21, 0xffff0000, v28
	v_pk_mul_f32 v[14:15], v[26:27], v[14:15]
	v_lshlrev_b32_e32 v22, 16, v29
	v_and_b32_e32 v23, 0xffff0000, v29
	v_pk_mul_f32 v[16:17], v[24:25], v[16:17]
	v_pk_mul_f32 v[24:25], v[68:69], s[22:23] op_sel_hi:[1,0]
	v_pk_mul_f32 v[26:27], v[66:67], s[22:23] op_sel_hi:[1,0]
	v_cvt_pk_bf16_f32 v14, v14, v15
	v_cvt_pk_bf16_f32 v15, v16, v17
	v_pk_mul_f32 v[22:23], v[24:25], v[22:23]
	v_pk_mul_f32 v[20:21], v[26:27], v[20:21]
	v_pk_mul_f32 v[24:25], v[62:63], s[22:23] op_sel_hi:[1,0]
	v_cvt_pk_bf16_f32 v16, v20, v21
	v_cvt_pk_bf16_f32 v17, v22, v23
	global_store_dwordx4 v[18:19], v[14:17], off offset:256
	s_waitcnt vmcnt(7)
	v_lshlrev_b32_e32 v18, 16, v32
	v_and_b32_e32 v19, 0xffff0000, v32
	v_lshlrev_b32_e32 v14, 16, v30
	v_and_b32_e32 v15, 0xffff0000, v30
	v_lshlrev_b32_e32 v16, 16, v31
	v_and_b32_e32 v17, 0xffff0000, v31
	v_pk_mul_f32 v[22:23], v[64:65], s[22:23] op_sel_hi:[1,0]
	v_pk_mul_f32 v[14:15], v[24:25], v[14:15]
	v_pk_mul_f32 v[24:25], v[58:59], s[22:23] op_sel_hi:[1,0]
	v_pk_mul_f32 v[16:17], v[22:23], v[16:17]
	v_pk_mul_f32 v[18:19], v[24:25], v[18:19]
	v_cvt_pk_bf16_f32 v14, v14, v15
	v_cvt_pk_bf16_f32 v15, v16, v17
	v_lshlrev_b32_e32 v20, 16, v33
	v_cvt_pk_bf16_f32 v16, v18, v19
	v_lshl_add_u64 v[18:19], s[16:17], 0, v[106:107]
	v_and_b32_e32 v21, 0xffff0000, v33
	v_pk_mul_f32 v[22:23], v[60:61], s[22:23] op_sel_hi:[1,0]
	v_lshl_add_u64 v[18:19], v[18:19], 0, v[10:11]
	v_pk_mul_f32 v[20:21], v[22:23], v[20:21]
	v_pk_mul_f32 v[26:27], v[54:55], s[22:23] op_sel_hi:[1,0]
	v_cvt_pk_bf16_f32 v17, v20, v21
	global_store_dwordx4 v[18:19], v[14:17], off
	s_waitcnt vmcnt(7)
	v_lshlrev_b32_e32 v20, 16, v100
	v_and_b32_e32 v21, 0xffff0000, v100
	v_lshlrev_b32_e32 v14, 16, v98
	v_and_b32_e32 v15, 0xffff0000, v98
	v_lshlrev_b32_e32 v16, 16, v99
	v_and_b32_e32 v17, 0xffff0000, v99
	v_pk_mul_f32 v[24:25], v[56:57], s[22:23] op_sel_hi:[1,0]
	v_pk_mul_f32 v[14:15], v[26:27], v[14:15]
	v_pk_mul_f32 v[26:27], v[50:51], s[22:23] op_sel_hi:[1,0]
	v_lshlrev_b32_e32 v22, 16, v101
	v_and_b32_e32 v23, 0xffff0000, v101
	v_pk_mul_f32 v[16:17], v[24:25], v[16:17]
	v_pk_mul_f32 v[24:25], v[52:53], s[22:23] op_sel_hi:[1,0]
	v_pk_mul_f32 v[20:21], v[26:27], v[20:21]
	v_cvt_pk_bf16_f32 v14, v14, v15
	v_cvt_pk_bf16_f32 v15, v16, v17
	v_pk_mul_f32 v[22:23], v[24:25], v[22:23]
	v_cvt_pk_bf16_f32 v16, v20, v21
	v_pk_mul_f32 v[20:21], v[46:47], s[22:23] op_sel_hi:[1,0]
	v_cvt_pk_bf16_f32 v17, v22, v23
	global_store_dwordx4 v[18:19], v[14:17], off offset:256
	v_pk_mul_f32 v[18:19], v[48:49], s[22:23] op_sel_hi:[1,0]
	v_lshl_add_u64 v[10:11], v[12:13], 0, v[10:11]
	s_waitcnt vmcnt(7)
	v_lshlrev_b32_e32 v14, 16, v6
	v_and_b32_e32 v15, 0xffff0000, v6
	v_lshlrev_b32_e32 v6, 16, v7
	v_and_b32_e32 v7, 0xffff0000, v7
	v_lshlrev_b32_e32 v16, 16, v8
	v_and_b32_e32 v17, 0xffff0000, v8
	v_lshlrev_b32_e32 v8, 16, v9
	v_and_b32_e32 v9, 0xffff0000, v9
	v_pk_mul_f32 v[18:19], v[18:19], v[6:7]
	v_pk_mul_f32 v[6:7], v[20:21], v[14:15]
	v_pk_mul_f32 v[14:15], v[44:45], s[22:23] op_sel_hi:[1,0]
	v_pk_mul_f32 v[20:21], v[42:43], s[22:23] op_sel_hi:[1,0]
	v_pk_mul_f32 v[14:15], v[14:15], v[8:9]
	v_pk_mul_f32 v[8:9], v[20:21], v[16:17]
	v_cvt_pk_bf16_f32 v6, v6, v7
	v_cvt_pk_bf16_f32 v7, v18, v19
	v_pk_mul_f32 v[12:13], v[40:41], s[22:23] op_sel_hi:[1,0]
	v_cvt_pk_bf16_f32 v8, v8, v9
	v_cvt_pk_bf16_f32 v9, v14, v15
	global_store_dwordx4 v[10:11], v[6:9], off
	v_pk_mul_f32 v[14:15], v[38:39], s[22:23] op_sel_hi:[1,0]
	s_waitcnt vmcnt(7)
	v_lshlrev_b32_e32 v6, 16, v2
	v_and_b32_e32 v7, 0xffff0000, v2
	v_lshlrev_b32_e32 v2, 16, v3
	v_and_b32_e32 v3, 0xffff0000, v3
	v_lshlrev_b32_e32 v8, 16, v4
	v_and_b32_e32 v9, 0xffff0000, v4
	v_lshlrev_b32_e32 v4, 16, v5
	v_and_b32_e32 v5, 0xffff0000, v5
	v_pk_mul_f32 v[12:13], v[12:13], v[2:3]
	v_pk_mul_f32 v[2:3], v[14:15], v[6:7]
	v_pk_mul_f32 v[6:7], v[36:37], s[22:23] op_sel_hi:[1,0]
	v_pk_mul_f32 v[14:15], v[34:35], s[22:23] op_sel_hi:[1,0]
	v_pk_mul_f32 v[6:7], v[6:7], v[4:5]
	v_pk_mul_f32 v[4:5], v[14:15], v[8:9]
	v_cvt_pk_bf16_f32 v2, v2, v3
	v_cvt_pk_bf16_f32 v3, v12, v13
	s_nop 0
	v_cvt_pk_bf16_f32 v4, v4, v5
	v_cvt_pk_bf16_f32 v5, v6, v7
	global_store_dwordx4 v[10:11], v[2:5], off offset:256
	s_cbranch_vccnz .LBB0_874
	s_andn2_b64 vcc, exec, s[6:7]
	s_cbranch_vccnz .LBB0_873
	s_barrier
	s_branch .LBB0_873
